# attention softmax row max: 7 clusters of 46 canonicalising v_max/v_max3 replaced by 16-instruction v_max3 chains over the same 32 score registers
# baseline (speedup 1.0000x reference)
.LBB0_162:
	ds_read_b128 v[32:35], v115
	ds_read_b128 v[98:101], v115 offset:32
	ds_read_b128 v[36:39], v115 offset:4608
	ds_read_b128 v[102:105], v115 offset:4640
	ds_read_b128 v[106:109], v115 offset:64
	ds_read_b128 v[110:113], v115 offset:96
	ds_read_b128 v[122:125], v115 offset:4672
	ds_read_b128 v[126:129], v115 offset:4704
	s_setprio 1
	s_setprio 0
	s_waitcnt lgkmcnt(7)
	v_mfma_f32_32x32x16_bf16 v[48:63], v[32:35], v[64:67], 0
	s_waitcnt lgkmcnt(5)
	v_mfma_f32_32x32x16_bf16 v[32:47], v[36:39], v[64:67], 0
	v_mfma_f32_32x32x16_bf16 v[48:63], v[98:101], v[68:71], v[48:63]
	s_waitcnt lgkmcnt(4)
	v_mfma_f32_32x32x16_bf16 v[32:47], v[102:105], v[68:71], v[32:47]
	s_waitcnt lgkmcnt(3)
	v_mfma_f32_32x32x16_bf16 v[48:63], v[106:109], v[72:75], v[48:63]
	s_waitcnt lgkmcnt(1)
	v_mfma_f32_32x32x16_bf16 v[32:47], v[122:125], v[72:75], v[32:47]
	v_mfma_f32_32x32x16_bf16 v[48:63], v[110:113], v[76:79], v[48:63]
	ds_read_b128 v[110:113], v119 offset:9216
	ds_read_b128 v[106:109], v119 offset:9248
	ds_read_b128 v[102:105], v119 offset:9280
	ds_read_b128 v[98:101], v119 offset:9312
	s_waitcnt lgkmcnt(4)
	v_mfma_f32_32x32x16_bf16 v[32:47], v[126:129], v[76:79], v[32:47]
	s_nop 11
	v_max3_f32 v96, v32, v33, v34
	v_max3_f32 v96, v96, v35, v36
	v_max3_f32 v96, v96, v37, v38
	v_max3_f32 v96, v96, v39, v40
	v_max3_f32 v96, v96, v41, v42
	v_max3_f32 v96, v96, v43, v44
	v_max3_f32 v96, v96, v45, v46
	v_max3_f32 v96, v96, v47, v48
	v_max3_f32 v96, v96, v49, v50
	v_max3_f32 v96, v96, v51, v52
	v_max3_f32 v96, v96, v53, v54
	v_max3_f32 v96, v96, v55, v56
	v_max3_f32 v96, v96, v57, v58
	v_max3_f32 v96, v96, v59, v60
	v_max3_f32 v96, v96, v61, v62
	v_max_f32_e32 v96, v96, v63
	v_mov_b32_e32 v122, v96
	s_nop 1
	v_permlane32_swap_b32_e32 v96, v122
	v_max3_f32 v122, v120, v96, v122
	v_add_f32_e32 v96, 0x41000000, v120
	v_cmp_gt_f32_e32 vcc, v122, v96
	s_cbranch_vccz .LBB0_164
	v_sub_f32_e32 v96, v120, v122
	v_exp_f32_e32 v96, v96
	s_nop 0
	v_mul_f32_e32 v121, v121, v96
	v_pk_mul_f32 v[14:15], v[14:15], v[96:97] op_sel_hi:[1,0]
	v_pk_mul_f32 v[12:13], v[12:13], v[96:97] op_sel_hi:[1,0]
	v_pk_mul_f32 v[10:11], v[10:11], v[96:97] op_sel_hi:[1,0]
	v_pk_mul_f32 v[8:9], v[8:9], v[96:97] op_sel_hi:[1,0]
	v_pk_mul_f32 v[6:7], v[6:7], v[96:97] op_sel_hi:[1,0]
	v_pk_mul_f32 v[4:5], v[4:5], v[96:97] op_sel_hi:[1,0]
	v_pk_mul_f32 v[2:3], v[2:3], v[96:97] op_sel_hi:[1,0]
	v_pk_mul_f32 v[0:1], v[0:1], v[96:97] op_sel_hi:[1,0]
	v_pk_mul_f32 v[30:31], v[30:31], v[96:97] op_sel_hi:[1,0]
	v_pk_mul_f32 v[28:29], v[28:29], v[96:97] op_sel_hi:[1,0]
	v_pk_mul_f32 v[26:27], v[26:27], v[96:97] op_sel_hi:[1,0]
	v_pk_mul_f32 v[24:25], v[24:25], v[96:97] op_sel_hi:[1,0]
	v_pk_mul_f32 v[22:23], v[22:23], v[96:97] op_sel_hi:[1,0]
	v_pk_mul_f32 v[20:21], v[20:21], v[96:97] op_sel_hi:[1,0]
	v_pk_mul_f32 v[18:19], v[18:19], v[96:97] op_sel_hi:[1,0]
	v_pk_mul_f32 v[16:17], v[16:17], v[96:97] op_sel_hi:[1,0]
	s_branch .LBB0_165

.LBB0_188:
	s_nop 9
	v_max3_f32 v96, v32, v33, v34
	v_max3_f32 v96, v96, v35, v36
	v_max3_f32 v96, v96, v37, v38
	v_max3_f32 v96, v96, v39, v40
	v_max3_f32 v96, v96, v41, v42
	v_max3_f32 v96, v96, v43, v44
	v_max3_f32 v96, v96, v45, v46
	v_max3_f32 v96, v96, v47, v48
	v_max3_f32 v96, v96, v49, v50
	v_max3_f32 v96, v96, v51, v52
	v_max3_f32 v96, v96, v53, v54
	v_max3_f32 v96, v96, v55, v56
	v_max3_f32 v96, v96, v57, v58
	v_max3_f32 v96, v96, v59, v60
	v_max3_f32 v96, v96, v61, v62
	v_max_f32_e32 v96, v96, v63
	v_mov_b32_e32 v127, v96
	s_nop 1
	v_permlane32_swap_b32_e32 v96, v127
	v_max3_f32 v127, v125, v96, v127
	v_add_f32_e32 v96, 0x41000000, v125
	v_cmp_gt_f32_e32 vcc, v127, v96
	s_cbranch_vccz .LBB0_190
	v_sub_f32_e32 v96, v125, v127
	v_exp_f32_e32 v96, v96
	v_mov_b32_e32 v125, v127
	v_mul_f32_e32 v115, v115, v96
	v_pk_mul_f32 v[14:15], v[14:15], v[96:97] op_sel_hi:[1,0]
	v_pk_mul_f32 v[12:13], v[12:13], v[96:97] op_sel_hi:[1,0]
	v_pk_mul_f32 v[10:11], v[10:11], v[96:97] op_sel_hi:[1,0]
	v_pk_mul_f32 v[8:9], v[8:9], v[96:97] op_sel_hi:[1,0]
	v_pk_mul_f32 v[6:7], v[6:7], v[96:97] op_sel_hi:[1,0]
	v_pk_mul_f32 v[4:5], v[4:5], v[96:97] op_sel_hi:[1,0]
	v_pk_mul_f32 v[2:3], v[2:3], v[96:97] op_sel_hi:[1,0]
	v_pk_mul_f32 v[0:1], v[0:1], v[96:97] op_sel_hi:[1,0]
	v_pk_mul_f32 v[30:31], v[30:31], v[96:97] op_sel_hi:[1,0]
	v_pk_mul_f32 v[28:29], v[28:29], v[96:97] op_sel_hi:[1,0]
	v_pk_mul_f32 v[26:27], v[26:27], v[96:97] op_sel_hi:[1,0]
	v_pk_mul_f32 v[24:25], v[24:25], v[96:97] op_sel_hi:[1,0]
	v_pk_mul_f32 v[22:23], v[22:23], v[96:97] op_sel_hi:[1,0]
	v_pk_mul_f32 v[20:21], v[20:21], v[96:97] op_sel_hi:[1,0]
	v_pk_mul_f32 v[18:19], v[18:19], v[96:97] op_sel_hi:[1,0]
	v_pk_mul_f32 v[16:17], v[16:17], v[96:97] op_sel_hi:[1,0]
	s_branch .LBB0_191

.LBB0_242:
	ds_read_b128 v[64:67], v183
	ds_read_b128 v[146:149], v183 offset:32
	ds_read_b128 v[68:71], v183 offset:4608
	ds_read_b128 v[150:153], v183 offset:4640
	ds_read_b128 v[154:157], v183 offset:64
	ds_read_b128 v[158:161], v183 offset:96
	ds_read_b128 v[166:169], v183 offset:4672
	ds_read_b128 v[188:191], v183 offset:4704
	s_setprio 1
	s_setprio 0
	s_waitcnt lgkmcnt(7)
	v_mfma_f32_32x32x16_bf16 v[80:95], v[64:67], v[98:101], 0
	s_waitcnt lgkmcnt(5)
	v_mfma_f32_32x32x16_bf16 v[64:79], v[68:71], v[98:101], 0
	v_mfma_f32_32x32x16_bf16 v[80:95], v[146:149], v[102:105], v[80:95]
	s_waitcnt lgkmcnt(4)
	v_mfma_f32_32x32x16_bf16 v[64:79], v[150:153], v[102:105], v[64:79]
	s_waitcnt lgkmcnt(3)
	v_mfma_f32_32x32x16_bf16 v[80:95], v[154:157], v[106:109], v[80:95]
	s_waitcnt lgkmcnt(1)
	v_mfma_f32_32x32x16_bf16 v[64:79], v[166:169], v[106:109], v[64:79]
	v_mfma_f32_32x32x16_bf16 v[80:95], v[158:161], v[110:113], v[80:95]
	ds_read_b128 v[158:161], v184 offset:18432
	ds_read_b128 v[154:157], v184 offset:18464
	ds_read_b128 v[150:153], v184 offset:18496
	ds_read_b128 v[146:149], v184 offset:18528
	s_waitcnt lgkmcnt(4)
	v_mfma_f32_32x32x16_bf16 v[64:79], v[188:191], v[110:113], v[64:79]
	s_nop 11
	v_max3_f32 v96, v64, v65, v66
	v_max3_f32 v96, v96, v67, v68
	v_max3_f32 v96, v96, v69, v70
	v_max3_f32 v96, v96, v71, v72
	v_max3_f32 v96, v96, v73, v74
	v_max3_f32 v96, v96, v75, v76
	v_max3_f32 v96, v96, v77, v78
	v_max3_f32 v96, v96, v79, v80
	v_max3_f32 v96, v96, v81, v82
	v_max3_f32 v96, v96, v83, v84
	v_max3_f32 v96, v96, v85, v86
	v_max3_f32 v96, v96, v87, v88
	v_max3_f32 v96, v96, v89, v90
	v_max3_f32 v96, v96, v91, v92
	v_max3_f32 v96, v96, v93, v94
	v_max_f32_e32 v96, v96, v95
	v_mov_b32_e32 v162, v96
	s_nop 1
	v_permlane32_swap_b32_e32 v96, v162
	v_max3_f32 v186, v187, v96, v162
	v_add_f32_e32 v96, 0x41000000, v187
	v_cmp_gt_f32_e32 vcc, v186, v96
	s_cbranch_vccz .LBB0_244
	v_sub_f32_e32 v96, v187, v186
	v_exp_f32_e32 v96, v96
	s_nop 0
	v_mul_f32_e32 v185, v185, v96
	v_pk_mul_f32 v[62:63], v[62:63], v[96:97] op_sel_hi:[1,0]
	v_pk_mul_f32 v[60:61], v[60:61], v[96:97] op_sel_hi:[1,0]
	v_pk_mul_f32 v[58:59], v[58:59], v[96:97] op_sel_hi:[1,0]
	v_pk_mul_f32 v[56:57], v[56:57], v[96:97] op_sel_hi:[1,0]
	v_pk_mul_f32 v[54:55], v[54:55], v[96:97] op_sel_hi:[1,0]
	v_pk_mul_f32 v[52:53], v[52:53], v[96:97] op_sel_hi:[1,0]
	v_pk_mul_f32 v[50:51], v[50:51], v[96:97] op_sel_hi:[1,0]
	v_pk_mul_f32 v[48:49], v[48:49], v[96:97] op_sel_hi:[1,0]
	v_pk_mul_f32 v[46:47], v[46:47], v[96:97] op_sel_hi:[1,0]
	v_pk_mul_f32 v[44:45], v[44:45], v[96:97] op_sel_hi:[1,0]
	v_pk_mul_f32 v[42:43], v[42:43], v[96:97] op_sel_hi:[1,0]
	v_pk_mul_f32 v[40:41], v[40:41], v[96:97] op_sel_hi:[1,0]
	v_pk_mul_f32 v[38:39], v[38:39], v[96:97] op_sel_hi:[1,0]
	v_pk_mul_f32 v[36:37], v[36:37], v[96:97] op_sel_hi:[1,0]
	v_pk_mul_f32 v[34:35], v[34:35], v[96:97] op_sel_hi:[1,0]
	v_pk_mul_f32 v[32:33], v[32:33], v[96:97] op_sel_hi:[1,0]
	v_pk_mul_f32 v[30:31], v[30:31], v[96:97] op_sel_hi:[1,0]
	v_pk_mul_f32 v[28:29], v[28:29], v[96:97] op_sel_hi:[1,0]
	v_pk_mul_f32 v[26:27], v[26:27], v[96:97] op_sel_hi:[1,0]
	v_pk_mul_f32 v[24:25], v[24:25], v[96:97] op_sel_hi:[1,0]
	v_pk_mul_f32 v[22:23], v[22:23], v[96:97] op_sel_hi:[1,0]
	v_pk_mul_f32 v[20:21], v[20:21], v[96:97] op_sel_hi:[1,0]
	v_pk_mul_f32 v[18:19], v[18:19], v[96:97] op_sel_hi:[1,0]
	v_pk_mul_f32 v[16:17], v[16:17], v[96:97] op_sel_hi:[1,0]
	v_pk_mul_f32 v[14:15], v[14:15], v[96:97] op_sel_hi:[1,0]
	v_pk_mul_f32 v[12:13], v[12:13], v[96:97] op_sel_hi:[1,0]
	v_pk_mul_f32 v[10:11], v[10:11], v[96:97] op_sel_hi:[1,0]
	v_pk_mul_f32 v[8:9], v[8:9], v[96:97] op_sel_hi:[1,0]
	v_pk_mul_f32 v[6:7], v[6:7], v[96:97] op_sel_hi:[1,0]
	v_pk_mul_f32 v[4:5], v[4:5], v[96:97] op_sel_hi:[1,0]
	v_pk_mul_f32 v[2:3], v[2:3], v[96:97] op_sel_hi:[1,0]
	v_pk_mul_f32 v[0:1], v[0:1], v[96:97] op_sel_hi:[1,0]
	s_branch .LBB0_245

.LBB0_247:
	v_add_f32_e32 v64, v80, v64
	v_add_f32_e32 v64, 0, v64
	v_add_f32_e32 v65, v81, v65
	v_add_f32_e32 v64, v65, v64
	v_add_f32_e32 v65, v82, v66
	v_add_f32_e32 v64, v65, v64
	v_add_f32_e32 v65, v83, v67
	v_add_f32_e32 v64, v65, v64
	v_add_f32_e32 v65, v84, v68
	v_add_f32_e32 v64, v65, v64
	v_add_f32_e32 v65, v85, v69
	v_add_f32_e32 v64, v65, v64
	v_add_f32_e32 v65, v86, v70
	v_add_f32_e32 v64, v65, v64
	v_add_f32_e32 v65, v87, v71
	v_add_f32_e32 v64, v65, v64
	v_add_f32_e32 v65, v88, v72
	v_add_f32_e32 v64, v65, v64
	v_add_f32_e32 v65, v89, v73
	v_add_f32_e32 v64, v65, v64
	v_add_f32_e32 v65, v90, v74
	v_add_f32_e32 v64, v65, v64
	v_add_f32_e32 v65, v91, v75
	v_add_f32_e32 v64, v65, v64
	v_add_f32_e32 v65, v92, v76
	v_add_f32_e32 v64, v65, v64
	v_add_f32_e32 v65, v93, v77
	v_add_f32_e32 v64, v65, v64
	v_add_f32_e32 v65, v94, v78
	v_add_f32_e32 v64, v65, v64
	v_add_f32_e32 v65, v95, v79
	v_add_f32_e32 v64, v65, v64
	v_add_f32_e32 v96, v185, v64
	ds_read_b128 v[64:67], v183 offset:41472
	ds_read_b128 v[68:71], v183 offset:36864
	ds_read_b128 v[146:149], v183 offset:36896
	ds_read_b128 v[150:153], v183 offset:41504
	ds_read_b128 v[154:157], v183 offset:36928
	ds_read_b128 v[158:161], v183 offset:41536
	ds_read_b128 v[166:169], v183 offset:36960
	ds_read_b128 v[188:191], v183 offset:41568
	s_setprio 1
	s_setprio 0
	s_waitcnt lgkmcnt(6)
	v_mfma_f32_32x32x16_bf16 v[80:95], v[68:71], v[98:101], 0
	v_mfma_f32_32x32x16_bf16 v[64:79], v[64:67], v[98:101], 0
	s_waitcnt lgkmcnt(5)
	v_mfma_f32_32x32x16_bf16 v[80:95], v[146:149], v[102:105], v[80:95]
	s_waitcnt lgkmcnt(4)
	v_mfma_f32_32x32x16_bf16 v[64:79], v[150:153], v[102:105], v[64:79]
	s_waitcnt lgkmcnt(3)
	v_mfma_f32_32x32x16_bf16 v[80:95], v[154:157], v[106:109], v[80:95]
	s_waitcnt lgkmcnt(2)
	v_mfma_f32_32x32x16_bf16 v[64:79], v[158:161], v[106:109], v[64:79]
	ds_read_b128 v[158:161], v184 offset:55296
	ds_read_b128 v[154:157], v184 offset:55328
	ds_read_b128 v[150:153], v184 offset:55360
	ds_read_b128 v[146:149], v184 offset:55392
	s_waitcnt lgkmcnt(5)
	v_mfma_f32_32x32x16_bf16 v[80:95], v[166:169], v[110:113], v[80:95]
	s_waitcnt lgkmcnt(4)
	v_mfma_f32_32x32x16_bf16 v[64:79], v[188:191], v[110:113], v[64:79]
	s_nop 11
	v_max3_f32 v162, v64, v65, v66
	v_max3_f32 v162, v162, v67, v68
	v_max3_f32 v162, v162, v69, v70
	v_max3_f32 v162, v162, v71, v72
	v_max3_f32 v162, v162, v73, v74
	v_max3_f32 v162, v162, v75, v76
	v_max3_f32 v162, v162, v77, v78
	v_max3_f32 v162, v162, v79, v80
	v_max3_f32 v162, v162, v81, v82
	v_max3_f32 v162, v162, v83, v84
	v_max3_f32 v162, v162, v85, v86
	v_max3_f32 v162, v162, v87, v88
	v_max3_f32 v162, v162, v89, v90
	v_max3_f32 v162, v162, v91, v92
	v_max3_f32 v162, v162, v93, v94
	v_max_f32_e32 v162, v162, v95
	v_mov_b32_e32 v163, v162
	s_nop 1
	v_permlane32_swap_b32_e32 v162, v163
	v_max3_f32 v187, v186, v162, v163
	v_add_f32_e32 v162, 0x41000000, v186
	v_cmp_gt_f32_e32 vcc, v187, v162
	s_cbranch_vccz .LBB0_249
	v_sub_f32_e32 v162, v186, v187
	v_exp_f32_e32 v162, v162
	s_nop 0
	v_mul_f32_e32 v96, v96, v162
	v_pk_mul_f32 v[62:63], v[62:63], v[162:163] op_sel_hi:[1,0]
	v_pk_mul_f32 v[60:61], v[60:61], v[162:163] op_sel_hi:[1,0]
	v_pk_mul_f32 v[58:59], v[58:59], v[162:163] op_sel_hi:[1,0]
	v_pk_mul_f32 v[56:57], v[56:57], v[162:163] op_sel_hi:[1,0]
	v_pk_mul_f32 v[54:55], v[54:55], v[162:163] op_sel_hi:[1,0]
	v_pk_mul_f32 v[52:53], v[52:53], v[162:163] op_sel_hi:[1,0]
	v_pk_mul_f32 v[50:51], v[50:51], v[162:163] op_sel_hi:[1,0]
	v_pk_mul_f32 v[48:49], v[48:49], v[162:163] op_sel_hi:[1,0]
	v_pk_mul_f32 v[46:47], v[46:47], v[162:163] op_sel_hi:[1,0]
	v_pk_mul_f32 v[44:45], v[44:45], v[162:163] op_sel_hi:[1,0]
	v_pk_mul_f32 v[42:43], v[42:43], v[162:163] op_sel_hi:[1,0]
	v_pk_mul_f32 v[40:41], v[40:41], v[162:163] op_sel_hi:[1,0]
	v_pk_mul_f32 v[38:39], v[38:39], v[162:163] op_sel_hi:[1,0]
	v_pk_mul_f32 v[36:37], v[36:37], v[162:163] op_sel_hi:[1,0]
	v_pk_mul_f32 v[34:35], v[34:35], v[162:163] op_sel_hi:[1,0]
	v_pk_mul_f32 v[32:33], v[32:33], v[162:163] op_sel_hi:[1,0]
	v_pk_mul_f32 v[30:31], v[30:31], v[162:163] op_sel_hi:[1,0]
	v_pk_mul_f32 v[28:29], v[28:29], v[162:163] op_sel_hi:[1,0]
	v_pk_mul_f32 v[26:27], v[26:27], v[162:163] op_sel_hi:[1,0]
	v_pk_mul_f32 v[24:25], v[24:25], v[162:163] op_sel_hi:[1,0]
	v_pk_mul_f32 v[22:23], v[22:23], v[162:163] op_sel_hi:[1,0]
	v_pk_mul_f32 v[20:21], v[20:21], v[162:163] op_sel_hi:[1,0]
	v_pk_mul_f32 v[18:19], v[18:19], v[162:163] op_sel_hi:[1,0]
	v_pk_mul_f32 v[16:17], v[16:17], v[162:163] op_sel_hi:[1,0]
	v_pk_mul_f32 v[14:15], v[14:15], v[162:163] op_sel_hi:[1,0]
	v_pk_mul_f32 v[12:13], v[12:13], v[162:163] op_sel_hi:[1,0]
	v_pk_mul_f32 v[10:11], v[10:11], v[162:163] op_sel_hi:[1,0]
	v_pk_mul_f32 v[8:9], v[8:9], v[162:163] op_sel_hi:[1,0]
	v_pk_mul_f32 v[6:7], v[6:7], v[162:163] op_sel_hi:[1,0]
	v_pk_mul_f32 v[4:5], v[4:5], v[162:163] op_sel_hi:[1,0]
	v_pk_mul_f32 v[2:3], v[2:3], v[162:163] op_sel_hi:[1,0]
	v_pk_mul_f32 v[0:1], v[0:1], v[162:163] op_sel_hi:[1,0]
	s_branch .LBB0_250

.LBB0_275:
	ds_read_b128 v[64:67], v183
	ds_read_b128 v[146:149], v183 offset:32
	ds_read_b128 v[68:71], v183 offset:4608
	ds_read_b128 v[150:153], v183 offset:4640
	ds_read_b128 v[154:157], v183 offset:64
	ds_read_b128 v[158:161], v183 offset:96
	ds_read_b128 v[166:169], v183 offset:4672
	ds_read_b128 v[188:191], v183 offset:4704
	s_setprio 1
	s_setprio 0
	s_waitcnt lgkmcnt(7)
	v_mfma_f32_32x32x16_bf16 v[80:95], v[64:67], v[98:101], 0
	s_waitcnt lgkmcnt(5)
	v_mfma_f32_32x32x16_bf16 v[64:79], v[68:71], v[98:101], 0
	v_mfma_f32_32x32x16_bf16 v[80:95], v[146:149], v[102:105], v[80:95]
	s_waitcnt lgkmcnt(4)
	v_mfma_f32_32x32x16_bf16 v[64:79], v[150:153], v[102:105], v[64:79]
	s_waitcnt lgkmcnt(3)
	v_mfma_f32_32x32x16_bf16 v[80:95], v[154:157], v[106:109], v[80:95]
	s_waitcnt lgkmcnt(1)
	v_mfma_f32_32x32x16_bf16 v[64:79], v[166:169], v[106:109], v[64:79]
	v_mfma_f32_32x32x16_bf16 v[80:95], v[158:161], v[110:113], v[80:95]
	ds_read_b128 v[158:161], v184 offset:18432
	ds_read_b128 v[154:157], v184 offset:18464
	ds_read_b128 v[150:153], v184 offset:18496
	ds_read_b128 v[146:149], v184 offset:18528
	s_waitcnt lgkmcnt(4)
	v_mfma_f32_32x32x16_bf16 v[64:79], v[188:191], v[110:113], v[64:79]
	s_nop 11
	v_max3_f32 v96, v64, v65, v66
	v_max3_f32 v96, v96, v67, v68
	v_max3_f32 v96, v96, v69, v70
	v_max3_f32 v96, v96, v71, v72
	v_max3_f32 v96, v96, v73, v74
	v_max3_f32 v96, v96, v75, v76
	v_max3_f32 v96, v96, v77, v78
	v_max3_f32 v96, v96, v79, v80
	v_max3_f32 v96, v96, v81, v82
	v_max3_f32 v96, v96, v83, v84
	v_max3_f32 v96, v96, v85, v86
	v_max3_f32 v96, v96, v87, v88
	v_max3_f32 v96, v96, v89, v90
	v_max3_f32 v96, v96, v91, v92
	v_max3_f32 v96, v96, v93, v94
	v_max_f32_e32 v96, v96, v95
	v_mov_b32_e32 v162, v96
	s_nop 1
	v_permlane32_swap_b32_e32 v96, v162
	v_max3_f32 v187, v186, v96, v162
	v_add_f32_e32 v96, 0x41000000, v186
	v_cmp_gt_f32_e32 vcc, v187, v96
	s_cbranch_vccz .LBB0_277
	v_sub_f32_e32 v96, v186, v187
	v_exp_f32_e32 v96, v96
	s_nop 0
	v_mul_f32_e32 v185, v185, v96
	v_pk_mul_f32 v[62:63], v[62:63], v[96:97] op_sel_hi:[1,0]
	v_pk_mul_f32 v[60:61], v[60:61], v[96:97] op_sel_hi:[1,0]
	v_pk_mul_f32 v[58:59], v[58:59], v[96:97] op_sel_hi:[1,0]
	v_pk_mul_f32 v[56:57], v[56:57], v[96:97] op_sel_hi:[1,0]
	v_pk_mul_f32 v[54:55], v[54:55], v[96:97] op_sel_hi:[1,0]
	v_pk_mul_f32 v[52:53], v[52:53], v[96:97] op_sel_hi:[1,0]
	v_pk_mul_f32 v[50:51], v[50:51], v[96:97] op_sel_hi:[1,0]
	v_pk_mul_f32 v[48:49], v[48:49], v[96:97] op_sel_hi:[1,0]
	v_pk_mul_f32 v[46:47], v[46:47], v[96:97] op_sel_hi:[1,0]
	v_pk_mul_f32 v[44:45], v[44:45], v[96:97] op_sel_hi:[1,0]
	v_pk_mul_f32 v[42:43], v[42:43], v[96:97] op_sel_hi:[1,0]
	v_pk_mul_f32 v[40:41], v[40:41], v[96:97] op_sel_hi:[1,0]
	v_pk_mul_f32 v[38:39], v[38:39], v[96:97] op_sel_hi:[1,0]
	v_pk_mul_f32 v[36:37], v[36:37], v[96:97] op_sel_hi:[1,0]
	v_pk_mul_f32 v[34:35], v[34:35], v[96:97] op_sel_hi:[1,0]
	v_pk_mul_f32 v[32:33], v[32:33], v[96:97] op_sel_hi:[1,0]
	v_pk_mul_f32 v[30:31], v[30:31], v[96:97] op_sel_hi:[1,0]
	v_pk_mul_f32 v[28:29], v[28:29], v[96:97] op_sel_hi:[1,0]
	v_pk_mul_f32 v[26:27], v[26:27], v[96:97] op_sel_hi:[1,0]
	v_pk_mul_f32 v[24:25], v[24:25], v[96:97] op_sel_hi:[1,0]
	v_pk_mul_f32 v[22:23], v[22:23], v[96:97] op_sel_hi:[1,0]
	v_pk_mul_f32 v[20:21], v[20:21], v[96:97] op_sel_hi:[1,0]
	v_pk_mul_f32 v[18:19], v[18:19], v[96:97] op_sel_hi:[1,0]
	v_pk_mul_f32 v[16:17], v[16:17], v[96:97] op_sel_hi:[1,0]
	v_pk_mul_f32 v[14:15], v[14:15], v[96:97] op_sel_hi:[1,0]
	v_pk_mul_f32 v[12:13], v[12:13], v[96:97] op_sel_hi:[1,0]
	v_pk_mul_f32 v[10:11], v[10:11], v[96:97] op_sel_hi:[1,0]
	v_pk_mul_f32 v[8:9], v[8:9], v[96:97] op_sel_hi:[1,0]
	v_pk_mul_f32 v[6:7], v[6:7], v[96:97] op_sel_hi:[1,0]
	v_pk_mul_f32 v[4:5], v[4:5], v[96:97] op_sel_hi:[1,0]
	v_pk_mul_f32 v[2:3], v[2:3], v[96:97] op_sel_hi:[1,0]
	v_pk_mul_f32 v[0:1], v[0:1], v[96:97] op_sel_hi:[1,0]
	s_branch .LBB0_278

.LBB0_285:
	v_add_f32_e32 v64, v80, v64
	v_add_f32_e32 v64, 0, v64
	v_add_f32_e32 v65, v81, v65
	v_add_f32_e32 v64, v65, v64
	v_add_f32_e32 v65, v82, v66
	v_add_f32_e32 v64, v65, v64
	v_add_f32_e32 v65, v83, v67
	v_add_f32_e32 v64, v65, v64
	v_add_f32_e32 v65, v84, v68
	v_add_f32_e32 v64, v65, v64
	v_add_f32_e32 v65, v85, v69
	v_add_f32_e32 v64, v65, v64
	v_add_f32_e32 v65, v86, v70
	v_add_f32_e32 v64, v65, v64
	v_add_f32_e32 v65, v87, v71
	v_add_f32_e32 v64, v65, v64
	v_add_f32_e32 v65, v88, v72
	v_add_f32_e32 v64, v65, v64
	v_add_f32_e32 v65, v89, v73
	v_add_f32_e32 v64, v65, v64
	v_add_f32_e32 v65, v90, v74
	v_add_f32_e32 v64, v65, v64
	v_add_f32_e32 v65, v91, v75
	v_add_f32_e32 v64, v65, v64
	v_add_f32_e32 v65, v92, v76
	v_add_f32_e32 v64, v65, v64
	v_add_f32_e32 v65, v93, v77
	v_add_f32_e32 v64, v65, v64
	v_add_f32_e32 v65, v94, v78
	v_add_f32_e32 v64, v65, v64
	v_add_f32_e32 v65, v95, v79
	v_add_f32_e32 v64, v65, v64
	v_add_f32_e32 v185, v185, v64
	ds_read_b128 v[64:67], v183 offset:41472
	ds_read_b128 v[68:71], v183 offset:36864
	ds_read_b128 v[146:149], v183 offset:36896
	ds_read_b128 v[150:153], v183 offset:41504
	ds_read_b128 v[154:157], v183 offset:36928
	ds_read_b128 v[158:161], v183 offset:41536
	ds_read_b128 v[166:169], v183 offset:36960
	ds_read_b128 v[188:191], v183 offset:41568
	s_setprio 1
	s_setprio 0
	s_waitcnt lgkmcnt(6)
	v_mfma_f32_32x32x16_bf16 v[80:95], v[68:71], v[98:101], 0
	v_mfma_f32_32x32x16_bf16 v[64:79], v[64:67], v[98:101], 0
	s_waitcnt lgkmcnt(5)
	v_mfma_f32_32x32x16_bf16 v[80:95], v[146:149], v[102:105], v[80:95]
	s_waitcnt lgkmcnt(4)
	v_mfma_f32_32x32x16_bf16 v[64:79], v[150:153], v[102:105], v[64:79]
	s_waitcnt lgkmcnt(3)
	v_mfma_f32_32x32x16_bf16 v[80:95], v[154:157], v[106:109], v[80:95]
	s_waitcnt lgkmcnt(2)
	v_mfma_f32_32x32x16_bf16 v[64:79], v[158:161], v[106:109], v[64:79]
	ds_read_b128 v[158:161], v184 offset:55296
	ds_read_b128 v[154:157], v184 offset:55328
	ds_read_b128 v[150:153], v184 offset:55360
	ds_read_b128 v[146:149], v184 offset:55392
	s_waitcnt lgkmcnt(5)
	v_mfma_f32_32x32x16_bf16 v[80:95], v[166:169], v[110:113], v[80:95]
	s_waitcnt lgkmcnt(4)
	v_mfma_f32_32x32x16_bf16 v[64:79], v[188:191], v[110:113], v[64:79]
	s_nop 11
	v_max3_f32 v96, v64, v65, v66
	v_max3_f32 v96, v96, v67, v68
	v_max3_f32 v96, v96, v69, v70
	v_max3_f32 v96, v96, v71, v72
	v_max3_f32 v96, v96, v73, v74
	v_max3_f32 v96, v96, v75, v76
	v_max3_f32 v96, v96, v77, v78
	v_max3_f32 v96, v96, v79, v80
	v_max3_f32 v96, v96, v81, v82
	v_max3_f32 v96, v96, v83, v84
	v_max3_f32 v96, v96, v85, v86
	v_max3_f32 v96, v96, v87, v88
	v_max3_f32 v96, v96, v89, v90
	v_max3_f32 v96, v96, v91, v92
	v_max3_f32 v96, v96, v93, v94
	v_max_f32_e32 v96, v96, v95
	v_mov_b32_e32 v162, v96
	s_nop 1
	v_permlane32_swap_b32_e32 v96, v162
	v_max3_f32 v186, v187, v96, v162
	v_add_f32_e32 v96, 0x41000000, v187
	v_cmp_gt_f32_e32 vcc, v186, v96
	s_cbranch_vccz .LBB0_287
	v_sub_f32_e32 v96, v187, v186
	v_exp_f32_e32 v96, v96
	s_nop 0
	v_mul_f32_e32 v185, v185, v96
	v_pk_mul_f32 v[62:63], v[62:63], v[96:97] op_sel_hi:[1,0]
	v_pk_mul_f32 v[60:61], v[60:61], v[96:97] op_sel_hi:[1,0]
	v_pk_mul_f32 v[58:59], v[58:59], v[96:97] op_sel_hi:[1,0]
	v_pk_mul_f32 v[56:57], v[56:57], v[96:97] op_sel_hi:[1,0]
	v_pk_mul_f32 v[54:55], v[54:55], v[96:97] op_sel_hi:[1,0]
	v_pk_mul_f32 v[52:53], v[52:53], v[96:97] op_sel_hi:[1,0]
	v_pk_mul_f32 v[50:51], v[50:51], v[96:97] op_sel_hi:[1,0]
	v_pk_mul_f32 v[48:49], v[48:49], v[96:97] op_sel_hi:[1,0]
	v_pk_mul_f32 v[46:47], v[46:47], v[96:97] op_sel_hi:[1,0]
	v_pk_mul_f32 v[44:45], v[44:45], v[96:97] op_sel_hi:[1,0]
	v_pk_mul_f32 v[42:43], v[42:43], v[96:97] op_sel_hi:[1,0]
	v_pk_mul_f32 v[40:41], v[40:41], v[96:97] op_sel_hi:[1,0]
	v_pk_mul_f32 v[38:39], v[38:39], v[96:97] op_sel_hi:[1,0]
	v_pk_mul_f32 v[36:37], v[36:37], v[96:97] op_sel_hi:[1,0]
	v_pk_mul_f32 v[34:35], v[34:35], v[96:97] op_sel_hi:[1,0]
	v_pk_mul_f32 v[32:33], v[32:33], v[96:97] op_sel_hi:[1,0]
	v_pk_mul_f32 v[30:31], v[30:31], v[96:97] op_sel_hi:[1,0]
	v_pk_mul_f32 v[28:29], v[28:29], v[96:97] op_sel_hi:[1,0]
	v_pk_mul_f32 v[26:27], v[26:27], v[96:97] op_sel_hi:[1,0]
	v_pk_mul_f32 v[24:25], v[24:25], v[96:97] op_sel_hi:[1,0]
	v_pk_mul_f32 v[22:23], v[22:23], v[96:97] op_sel_hi:[1,0]
	v_pk_mul_f32 v[20:21], v[20:21], v[96:97] op_sel_hi:[1,0]
	v_pk_mul_f32 v[18:19], v[18:19], v[96:97] op_sel_hi:[1,0]
	v_pk_mul_f32 v[16:17], v[16:17], v[96:97] op_sel_hi:[1,0]
	v_pk_mul_f32 v[14:15], v[14:15], v[96:97] op_sel_hi:[1,0]
	v_pk_mul_f32 v[12:13], v[12:13], v[96:97] op_sel_hi:[1,0]
	v_pk_mul_f32 v[10:11], v[10:11], v[96:97] op_sel_hi:[1,0]
	v_pk_mul_f32 v[8:9], v[8:9], v[96:97] op_sel_hi:[1,0]
	v_pk_mul_f32 v[6:7], v[6:7], v[96:97] op_sel_hi:[1,0]
	v_pk_mul_f32 v[4:5], v[4:5], v[96:97] op_sel_hi:[1,0]
	v_pk_mul_f32 v[2:3], v[2:3], v[96:97] op_sel_hi:[1,0]
	v_pk_mul_f32 v[0:1], v[0:1], v[96:97] op_sel_hi:[1,0]
	s_branch .LBB0_288
